# GEMM unit start: accumulators zeroed with 64 packed moves (v_pk_mov_b32) instead of 128 moves
# speedup vs baseline: 1.0156x; 1.0055x over previous
; #define PG8_STAGE(bufoff, gbase, voff) do { _Pragma("unroll") for (int _i = 0; _i < 2; ++_i) \
;         __builtin_amdgcn_global_load_lds((const unsigned*)((const char*)(gbase) + (voff)[_i]), (LAS unsigned*)(lds + (bufoff) + ldsw + _i * 8192), 16, 0, 0); } while (0)
; #define PG8_WAIT_V(n) asm volatile("s_waitcnt vmcnt(" #n ")" ::: "memory")
; #define PG8_BAR __builtin_amdgcn_s_barrier()
; template <class Epi>
; __device__ __forceinline__ void gemm_phase(LAS unsigned char* lds, const Gemm g, const StaticOrder& S, const Epi& E) {
;     ...
;     f32x4 acc[2][2][4][2];
; #pragma unroll
;     for (int a = 0; a < 2; ++a)
; #pragma unroll
;         for (int b = 0; b < 2; ++b)
; #pragma unroll
;             for (int m = 0; m < 4; ++m)
; #pragma unroll
;                 for (int n = 0; n < 2; ++n) acc[a][b][m][n] = (f32x4){0.f, 0.f, 0.f, 0.f};
;     bf16x8 At[4][2], B0[2][2], B1[2][2];
;     const char* cA = (const char*)g.A + (size_t)cur.pm * tstepA + (size_t)cur.pn * g.a_pn_off * 2; const char* cB = (const char*)g.Bt + (size_t)cur.pn * tstepB;
;     PG8_STAGE(PG8_SB(0, 0), cB, voffB); PG8_STAGE(PG8_SA(0, 0), cA, voffA); PG8_STAGE(PG8_SB(0, 1), cB + hstepB, voffB); PG8_STAGE(PG8_SA(0, 1), cA + hstepA, voffA);
;     if (wr == 1) PG8_BAR;
;     PG8_WAIT_V(4); PG8_BAR;
;     PG8_STAGE(PG8_SB(1, 0), cB + kstep, voffB); PG8_STAGE(PG8_SA(1, 0), cA + kstep, voffA); PG8_STAGE(PG8_SB(1, 1), cB + hstepB + kstep, voffB);
;     PG8_WAIT_V(6); PG8_BAR;
;     for (;;) {
;         const bool has_next = S.next(ui + 1, nxt);
;         const char* nA = has_next ? (const char*)g.A + (size_t)nxt.pm * tstepA + (size_t)nxt.pn * g.a_pn_off * 2 : cA; const char* nB = has_next ? (const char*)g.Bt + (size_t)nxt.pn * tstepB : cB;
;         for (int t = 0; t < nt; t += 2) {
;             const bool last = (t == nt - 2);
;             const char* a1 = cA + (size_t)(t + 1) * kstep;
;             const char* a2 = last ? nA : cA + (size_t)(t + 2) * kstep; const char* b2 = last ? nB : cB + (size_t)(t + 2) * kstep;
.LBB0_1440:
	s_ashr_i32 s29, s28, 31
	s_lshl_b64 s[30:31], s[28:29], 19
	s_add_u32 s29, s74, s30
	s_addc_u32 s34, s75, s31
	s_ashr_i32 s27, s26, 31
	s_lshl_b64 s[30:31], s[26:27], 9
	s_add_u32 s30, s29, s30
	s_addc_u32 s31, s34, s31
	s_lshl_b64 s[34:35], s[26:27], 17
	s_add_u32 s34, s54, s34
	v_pk_mov_b32 v[0:1], 0, 0
	v_cmp_lt_i64_e64 s[10:11], s[10:11], v[188:189]
	s_addc_u32 s35, s55, s35
	s_andn2_b64 vcc, exec, s[24:25]
	v_pk_mov_b32 v[2:3], 0, 0
	v_pk_mov_b32 v[4:5], 0, 0
	v_pk_mov_b32 v[6:7], 0, 0
	v_pk_mov_b32 v[8:9], 0, 0
	v_pk_mov_b32 v[10:11], 0, 0
	v_pk_mov_b32 v[12:13], 0, 0
	v_pk_mov_b32 v[14:15], 0, 0
	v_pk_mov_b32 v[16:17], 0, 0
	v_pk_mov_b32 v[18:19], 0, 0
	v_pk_mov_b32 v[20:21], 0, 0
	v_pk_mov_b32 v[22:23], 0, 0
	v_pk_mov_b32 v[24:25], 0, 0
	v_pk_mov_b32 v[26:27], 0, 0
	v_pk_mov_b32 v[28:29], 0, 0
	v_pk_mov_b32 v[30:31], 0, 0
	v_pk_mov_b32 v[32:33], 0, 0
	v_pk_mov_b32 v[34:35], 0, 0
	v_pk_mov_b32 v[36:37], 0, 0
	v_pk_mov_b32 v[38:39], 0, 0
	v_pk_mov_b32 v[40:41], 0, 0
	v_pk_mov_b32 v[42:43], 0, 0
	v_pk_mov_b32 v[44:45], 0, 0
	v_pk_mov_b32 v[46:47], 0, 0
	v_pk_mov_b32 v[48:49], 0, 0
	v_pk_mov_b32 v[50:51], 0, 0
	v_pk_mov_b32 v[52:53], 0, 0
	v_pk_mov_b32 v[54:55], 0, 0
	v_pk_mov_b32 v[56:57], 0, 0
	v_pk_mov_b32 v[58:59], 0, 0
	v_pk_mov_b32 v[60:61], 0, 0
	v_pk_mov_b32 v[62:63], 0, 0
	v_pk_mov_b32 v[64:65], 0, 0
	v_pk_mov_b32 v[66:67], 0, 0
	v_pk_mov_b32 v[68:69], 0, 0
	v_pk_mov_b32 v[70:71], 0, 0
	v_pk_mov_b32 v[72:73], 0, 0
	v_pk_mov_b32 v[74:75], 0, 0
	v_pk_mov_b32 v[76:77], 0, 0
	v_pk_mov_b32 v[78:79], 0, 0
	v_pk_mov_b32 v[80:81], 0, 0
	v_pk_mov_b32 v[82:83], 0, 0
	v_pk_mov_b32 v[84:85], 0, 0
	v_pk_mov_b32 v[86:87], 0, 0
	v_pk_mov_b32 v[88:89], 0, 0
	v_pk_mov_b32 v[90:91], 0, 0
	v_pk_mov_b32 v[92:93], 0, 0
	v_pk_mov_b32 v[94:95], 0, 0
	v_pk_mov_b32 v[96:97], 0, 0
	v_pk_mov_b32 v[98:99], 0, 0
	v_pk_mov_b32 v[100:101], 0, 0
	v_pk_mov_b32 v[102:103], 0, 0
	v_pk_mov_b32 v[104:105], 0, 0
	v_pk_mov_b32 v[106:107], 0, 0
	v_pk_mov_b32 v[108:109], 0, 0
	v_pk_mov_b32 v[110:111], 0, 0
	v_pk_mov_b32 v[112:113], 0, 0
	v_pk_mov_b32 v[114:115], 0, 0
	v_pk_mov_b32 v[116:117], 0, 0
	v_pk_mov_b32 v[118:119], 0, 0
	v_pk_mov_b32 v[120:121], 0, 0
	v_pk_mov_b32 v[122:123], 0, 0
	v_pk_mov_b32 v[124:125], 0, 0
	v_pk_mov_b32 v[126:127], 0, 0
	s_waitcnt vmcnt(0)
	s_waitcnt lgkmcnt(0)
	s_cbranch_vccnz .LBB0_1443
	s_and_b64 s[10:11], s[10:11], exec
	s_cselect_b32 s27, s31, s43
	s_cselect_b32 s29, s30, s42
	s_cselect_b32 s64, s35, s41
	s_cselect_b32 s65, s34, s40
	s_add_u32 s10, s42, 0x40080
	s_addc_u32 s11, s43, 0
	s_add_u32 s80, s40, 0x100
	s_addc_u32 s81, s41, 0
	s_mov_b32 s40, 0

; #define PG8_STAGE(bufoff, gbase, voff) do { _Pragma("unroll") for (int _i = 0; _i < 2; ++_i) \
;         __builtin_amdgcn_global_load_lds((const unsigned*)((const char*)(gbase) + (voff)[_i]), (LAS unsigned*)(lds + (bufoff) + ldsw + _i * 8192), 16, 0, 0); } while (0)
; #define PG8_WAIT_V(n) asm volatile("s_waitcnt vmcnt(" #n ")" ::: "memory")
; #define PG8_BAR __builtin_amdgcn_s_barrier()
; template <class Epi>
; __device__ __forceinline__ void gemm_phase(LAS unsigned char* lds, const Gemm g, const StaticOrder& S, const Epi& E) {
;     ...
;     f32x4 acc[2][2][4][2];
; #pragma unroll
;     for (int a = 0; a < 2; ++a)
; #pragma unroll
;         for (int b = 0; b < 2; ++b)
; #pragma unroll
;             for (int m = 0; m < 4; ++m)
; #pragma unroll
;                 for (int n = 0; n < 2; ++n) acc[a][b][m][n] = (f32x4){0.f, 0.f, 0.f, 0.f};
;     bf16x8 At[4][2], B0[2][2], B1[2][2];
;     const char* cA = (const char*)g.A + (size_t)cur.pm * tstepA + (size_t)cur.pn * g.a_pn_off * 2; const char* cB = (const char*)g.Bt + (size_t)cur.pn * tstepB;
;     PG8_STAGE(PG8_SB(0, 0), cB, voffB); PG8_STAGE(PG8_SA(0, 0), cA, voffA); PG8_STAGE(PG8_SB(0, 1), cB + hstepB, voffB); PG8_STAGE(PG8_SA(0, 1), cA + hstepA, voffA);
;     if (wr == 1) PG8_BAR;
;     PG8_WAIT_V(4); PG8_BAR;
;     PG8_STAGE(PG8_SB(1, 0), cB + kstep, voffB); PG8_STAGE(PG8_SA(1, 0), cA + kstep, voffA); PG8_STAGE(PG8_SB(1, 1), cB + hstepB + kstep, voffB);
;     PG8_WAIT_V(6); PG8_BAR;
;     for (;;) {
;         const bool has_next = S.next(ui + 1, nxt);
;         const char* nA = has_next ? (const char*)g.A + (size_t)nxt.pm * tstepA + (size_t)nxt.pn * g.a_pn_off * 2 : cA; const char* nB = has_next ? (const char*)g.Bt + (size_t)nxt.pn * tstepB : cB;
;         for (int t = 0; t < nt; t += 2) {
;             const bool last = (t == nt - 2);
;             const char* a1 = cA + (size_t)(t + 1) * kstep;
;             const char* a2 = last ? nA : cA + (size_t)(t + 2) * kstep; const char* b2 = last ? nB : cB + (size_t)(t + 2) * kstep;
.LBB0_1542:
	s_ashr_i32 s17, s16, 31
	s_lshl_b64 s[18:19], s[16:17], 19
	s_add_u32 s18, s70, s18
	s_addc_u32 s19, s71, s19
	s_ashr_i32 s15, s14, 31
	s_lshl_b64 s[22:23], s[14:15], 19
	s_add_u32 s22, s31, s22
	v_pk_mov_b32 v[0:1], 0, 0
	v_cmp_lt_i64_e64 s[8:9], s[8:9], v[140:141]
	s_addc_u32 s23, s34, s23
	s_andn2_b64 vcc, exec, s[12:13]
	v_pk_mov_b32 v[2:3], 0, 0
	v_pk_mov_b32 v[4:5], 0, 0
	v_pk_mov_b32 v[6:7], 0, 0
	v_pk_mov_b32 v[8:9], 0, 0
	v_pk_mov_b32 v[10:11], 0, 0
	v_pk_mov_b32 v[12:13], 0, 0
	v_pk_mov_b32 v[14:15], 0, 0
	v_pk_mov_b32 v[16:17], 0, 0
	v_pk_mov_b32 v[18:19], 0, 0
	v_pk_mov_b32 v[20:21], 0, 0
	v_pk_mov_b32 v[22:23], 0, 0
	v_pk_mov_b32 v[24:25], 0, 0
	v_pk_mov_b32 v[26:27], 0, 0
	v_pk_mov_b32 v[28:29], 0, 0
	v_pk_mov_b32 v[30:31], 0, 0
	v_pk_mov_b32 v[32:33], 0, 0
	v_pk_mov_b32 v[34:35], 0, 0
	v_pk_mov_b32 v[36:37], 0, 0
	v_pk_mov_b32 v[38:39], 0, 0
	v_pk_mov_b32 v[40:41], 0, 0
	v_pk_mov_b32 v[42:43], 0, 0
	v_pk_mov_b32 v[44:45], 0, 0
	v_pk_mov_b32 v[46:47], 0, 0
	v_pk_mov_b32 v[48:49], 0, 0
	v_pk_mov_b32 v[50:51], 0, 0
	v_pk_mov_b32 v[52:53], 0, 0
	v_pk_mov_b32 v[54:55], 0, 0
	v_pk_mov_b32 v[56:57], 0, 0
	v_pk_mov_b32 v[58:59], 0, 0
	v_pk_mov_b32 v[60:61], 0, 0
	v_pk_mov_b32 v[62:63], 0, 0
	v_pk_mov_b32 v[64:65], 0, 0
	v_pk_mov_b32 v[66:67], 0, 0
	v_pk_mov_b32 v[68:69], 0, 0
	v_pk_mov_b32 v[70:71], 0, 0
	v_pk_mov_b32 v[72:73], 0, 0
	v_pk_mov_b32 v[74:75], 0, 0
	v_pk_mov_b32 v[76:77], 0, 0
	v_pk_mov_b32 v[78:79], 0, 0
	v_pk_mov_b32 v[80:81], 0, 0
	v_pk_mov_b32 v[82:83], 0, 0
	v_pk_mov_b32 v[84:85], 0, 0
	v_pk_mov_b32 v[86:87], 0, 0
	v_pk_mov_b32 v[88:89], 0, 0
	v_pk_mov_b32 v[90:91], 0, 0
	v_pk_mov_b32 v[92:93], 0, 0
	v_pk_mov_b32 v[94:95], 0, 0
	v_pk_mov_b32 v[96:97], 0, 0
	v_pk_mov_b32 v[98:99], 0, 0
	v_pk_mov_b32 v[100:101], 0, 0
	v_pk_mov_b32 v[102:103], 0, 0
	v_pk_mov_b32 v[104:105], 0, 0
	v_pk_mov_b32 v[106:107], 0, 0
	v_pk_mov_b32 v[108:109], 0, 0
	v_pk_mov_b32 v[110:111], 0, 0
	v_pk_mov_b32 v[112:113], 0, 0
	v_pk_mov_b32 v[114:115], 0, 0
	v_pk_mov_b32 v[116:117], 0, 0
	v_pk_mov_b32 v[118:119], 0, 0
	v_pk_mov_b32 v[120:121], 0, 0
	v_pk_mov_b32 v[122:123], 0, 0
	v_pk_mov_b32 v[124:125], 0, 0
	v_pk_mov_b32 v[126:127], 0, 0
	s_waitcnt vmcnt(0)
	s_cbranch_vccnz .LBB0_1535
	s_and_b64 s[8:9], s[8:9], exec
	s_cselect_b32 s15, s19, s29
	s_cselect_b32 s17, s18, s28
	s_cselect_b32 s63, s23, s27
	s_cselect_b32 s64, s22, s26
	s_add_u32 s8, s28, 0x40080
	s_addc_u32 s9, s29, 0
	s_add_u32 s65, s26, 0x100
	s_addc_u32 s76, s27, 0
	s_mov_b32 s26, 0

; #define PG8_STAGE(bufoff, gbase, voff) do { _Pragma("unroll") for (int _i = 0; _i < 2; ++_i) \
;         __builtin_amdgcn_global_load_lds((const unsigned*)((const char*)(gbase) + (voff)[_i]), (LAS unsigned*)(lds + (bufoff) + ldsw + _i * 8192), 16, 0, 0); } while (0)
; #define PG8_WAIT_V(n) asm volatile("s_waitcnt vmcnt(" #n ")" ::: "memory")
; #define PG8_BAR __builtin_amdgcn_s_barrier()
; template <class Epi>
; __device__ __forceinline__ void gemm_phase(LAS unsigned char* lds, const Gemm g, const StaticOrder& S, const Epi& E) {
;     ...
;     f32x4 acc[2][2][4][2];
; #pragma unroll
;     for (int a = 0; a < 2; ++a)
; #pragma unroll
;         for (int b = 0; b < 2; ++b)
; #pragma unroll
;             for (int m = 0; m < 4; ++m)
; #pragma unroll
;                 for (int n = 0; n < 2; ++n) acc[a][b][m][n] = (f32x4){0.f, 0.f, 0.f, 0.f};
;     bf16x8 At[4][2], B0[2][2], B1[2][2];
;     const char* cA = (const char*)g.A + (size_t)cur.pm * tstepA + (size_t)cur.pn * g.a_pn_off * 2; const char* cB = (const char*)g.Bt + (size_t)cur.pn * tstepB;
;     PG8_STAGE(PG8_SB(0, 0), cB, voffB); PG8_STAGE(PG8_SA(0, 0), cA, voffA); PG8_STAGE(PG8_SB(0, 1), cB + hstepB, voffB); PG8_STAGE(PG8_SA(0, 1), cA + hstepA, voffA);
;     if (wr == 1) PG8_BAR;
;     PG8_WAIT_V(4); PG8_BAR;
;     PG8_STAGE(PG8_SB(1, 0), cB + kstep, voffB); PG8_STAGE(PG8_SA(1, 0), cA + kstep, voffA); PG8_STAGE(PG8_SB(1, 1), cB + hstepB + kstep, voffB);
;     PG8_WAIT_V(6); PG8_BAR;
;     for (;;) {
;         const bool has_next = S.next(ui + 1, nxt);
;         const char* nA = has_next ? (const char*)g.A + (size_t)nxt.pm * tstepA + (size_t)nxt.pn * g.a_pn_off * 2 : cA; const char* nB = has_next ? (const char*)g.Bt + (size_t)nxt.pn * tstepB : cB;
;         for (int t = 0; t < nt; t += 2) {
;             const bool last = (t == nt - 2);
;             const char* a1 = cA + (size_t)(t + 1) * kstep;
;             const char* a2 = last ? nA : cA + (size_t)(t + 2) * kstep; const char* b2 = last ? nB : cB + (size_t)(t + 2) * kstep;
.LBB0_1564:
	s_ashr_i32 s21, s20, 31
	s_lshl_b64 s[22:23], s[20:21], 17
	s_add_u32 s22, s68, s22
	s_addc_u32 s23, s69, s23
	s_ashr_i32 s19, s18, 31
	s_lshl_b64 s[24:25], s[18:19], 17
	s_add_u32 s24, s12, s24
	v_pk_mov_b32 v[0:1], 0, 0
	v_cmp_lt_i64_e64 s[10:11], s[10:11], v[140:141]
	s_addc_u32 s25, s13, s25
	s_and_b64 vcc, exec, s[6:7]
	v_pk_mov_b32 v[2:3], 0, 0
	v_pk_mov_b32 v[4:5], 0, 0
	v_pk_mov_b32 v[6:7], 0, 0
	v_pk_mov_b32 v[8:9], 0, 0
	v_pk_mov_b32 v[10:11], 0, 0
	v_pk_mov_b32 v[12:13], 0, 0
	v_pk_mov_b32 v[14:15], 0, 0
	v_pk_mov_b32 v[16:17], 0, 0
	v_pk_mov_b32 v[18:19], 0, 0
	v_pk_mov_b32 v[20:21], 0, 0
	v_pk_mov_b32 v[22:23], 0, 0
	v_pk_mov_b32 v[24:25], 0, 0
	v_pk_mov_b32 v[26:27], 0, 0
	v_pk_mov_b32 v[28:29], 0, 0
	v_pk_mov_b32 v[30:31], 0, 0
	v_pk_mov_b32 v[32:33], 0, 0
	v_pk_mov_b32 v[34:35], 0, 0
	v_pk_mov_b32 v[36:37], 0, 0
	v_pk_mov_b32 v[38:39], 0, 0
	v_pk_mov_b32 v[40:41], 0, 0
	v_pk_mov_b32 v[42:43], 0, 0
	v_pk_mov_b32 v[44:45], 0, 0
	v_pk_mov_b32 v[46:47], 0, 0
	v_pk_mov_b32 v[48:49], 0, 0
	v_pk_mov_b32 v[50:51], 0, 0
	v_pk_mov_b32 v[52:53], 0, 0
	v_pk_mov_b32 v[54:55], 0, 0
	v_pk_mov_b32 v[56:57], 0, 0
	v_pk_mov_b32 v[58:59], 0, 0
	v_pk_mov_b32 v[60:61], 0, 0
	v_pk_mov_b32 v[62:63], 0, 0
	v_pk_mov_b32 v[64:65], 0, 0
	v_pk_mov_b32 v[66:67], 0, 0
	v_pk_mov_b32 v[68:69], 0, 0
	v_pk_mov_b32 v[70:71], 0, 0
	v_pk_mov_b32 v[72:73], 0, 0
	v_pk_mov_b32 v[74:75], 0, 0
	v_pk_mov_b32 v[76:77], 0, 0
	v_pk_mov_b32 v[78:79], 0, 0
	v_pk_mov_b32 v[80:81], 0, 0
	v_pk_mov_b32 v[82:83], 0, 0
	v_pk_mov_b32 v[84:85], 0, 0
	v_pk_mov_b32 v[86:87], 0, 0
	v_pk_mov_b32 v[88:89], 0, 0
	v_pk_mov_b32 v[90:91], 0, 0
	v_pk_mov_b32 v[92:93], 0, 0
	v_pk_mov_b32 v[94:95], 0, 0
	v_pk_mov_b32 v[96:97], 0, 0
	v_pk_mov_b32 v[98:99], 0, 0
	v_pk_mov_b32 v[100:101], 0, 0
	v_pk_mov_b32 v[102:103], 0, 0
	v_pk_mov_b32 v[104:105], 0, 0
	v_pk_mov_b32 v[106:107], 0, 0
	v_pk_mov_b32 v[108:109], 0, 0
	v_pk_mov_b32 v[110:111], 0, 0
	v_pk_mov_b32 v[112:113], 0, 0
	v_pk_mov_b32 v[114:115], 0, 0
	v_pk_mov_b32 v[116:117], 0, 0
	v_pk_mov_b32 v[118:119], 0, 0
	v_pk_mov_b32 v[120:121], 0, 0
	v_pk_mov_b32 v[122:123], 0, 0
	v_pk_mov_b32 v[124:125], 0, 0
	v_pk_mov_b32 v[126:127], 0, 0
	s_cbranch_vccnz .LBB0_1557
	s_and_b64 s[10:11], s[10:11], exec
	s_cselect_b32 s19, s23, s29
	s_cselect_b32 s21, s22, s28
	s_cselect_b32 s60, s25, s27
	s_cselect_b32 s61, s24, s26
	s_add_u32 s10, s28, 0x10080
	s_addc_u32 s11, s29, 0
	s_add_u32 s62, s26, 0x100
	s_addc_u32 s63, s27, 0
	s_mov_b32 s26, 0

; #define PG8_STAGE(bufoff, gbase, voff) do { _Pragma("unroll") for (int _i = 0; _i < 2; ++_i) \
;         __builtin_amdgcn_global_load_lds((const unsigned*)((const char*)(gbase) + (voff)[_i]), (LAS unsigned*)(lds + (bufoff) + ldsw + _i * 8192), 16, 0, 0); } while (0)
; #define PG8_WAIT_V(n) asm volatile("s_waitcnt vmcnt(" #n ")" ::: "memory")
; #define PG8_BAR __builtin_amdgcn_s_barrier()
; template <class Epi>
; __device__ __forceinline__ void gemm_phase(LAS unsigned char* lds, const Gemm g, const StaticOrder& S, const Epi& E) {
;     ...
;     f32x4 acc[2][2][4][2];
; #pragma unroll
;     for (int a = 0; a < 2; ++a)
; #pragma unroll
;         for (int b = 0; b < 2; ++b)
; #pragma unroll
;             for (int m = 0; m < 4; ++m)
; #pragma unroll
;                 for (int n = 0; n < 2; ++n) acc[a][b][m][n] = (f32x4){0.f, 0.f, 0.f, 0.f};
;     bf16x8 At[4][2], B0[2][2], B1[2][2];
;     const char* cA = (const char*)g.A + (size_t)cur.pm * tstepA + (size_t)cur.pn * g.a_pn_off * 2; const char* cB = (const char*)g.Bt + (size_t)cur.pn * tstepB;
;     PG8_STAGE(PG8_SB(0, 0), cB, voffB); PG8_STAGE(PG8_SA(0, 0), cA, voffA); PG8_STAGE(PG8_SB(0, 1), cB + hstepB, voffB); PG8_STAGE(PG8_SA(0, 1), cA + hstepA, voffA);
;     if (wr == 1) PG8_BAR;
;     PG8_WAIT_V(4); PG8_BAR;
;     PG8_STAGE(PG8_SB(1, 0), cB + kstep, voffB); PG8_STAGE(PG8_SA(1, 0), cA + kstep, voffA); PG8_STAGE(PG8_SB(1, 1), cB + hstepB + kstep, voffB);
;     PG8_WAIT_V(6); PG8_BAR;
;     for (;;) {
;         const bool has_next = S.next(ui + 1, nxt);
;         const char* nA = has_next ? (const char*)g.A + (size_t)nxt.pm * tstepA + (size_t)nxt.pn * g.a_pn_off * 2 : cA; const char* nB = has_next ? (const char*)g.Bt + (size_t)nxt.pn * tstepB : cB;
;         for (int t = 0; t < nt; t += 2) {
.LBB0_1651:
	v_pk_mov_b32 v[0:1], 0, 0
	s_andn2_b64 vcc, exec, s[20:21]
	v_pk_mov_b32 v[2:3], 0, 0
	v_pk_mov_b32 v[4:5], 0, 0
	v_pk_mov_b32 v[6:7], 0, 0
	v_pk_mov_b32 v[8:9], 0, 0
	v_pk_mov_b32 v[10:11], 0, 0
	v_pk_mov_b32 v[12:13], 0, 0
	v_pk_mov_b32 v[14:15], 0, 0
	v_pk_mov_b32 v[16:17], 0, 0
	v_pk_mov_b32 v[18:19], 0, 0
	v_pk_mov_b32 v[20:21], 0, 0
	v_pk_mov_b32 v[22:23], 0, 0
	v_pk_mov_b32 v[24:25], 0, 0
	v_pk_mov_b32 v[26:27], 0, 0
	v_pk_mov_b32 v[28:29], 0, 0
	v_pk_mov_b32 v[30:31], 0, 0
	v_pk_mov_b32 v[32:33], 0, 0
	v_pk_mov_b32 v[34:35], 0, 0
	v_pk_mov_b32 v[36:37], 0, 0
	v_pk_mov_b32 v[38:39], 0, 0
	v_pk_mov_b32 v[40:41], 0, 0
	v_pk_mov_b32 v[42:43], 0, 0
	v_pk_mov_b32 v[44:45], 0, 0
	v_pk_mov_b32 v[46:47], 0, 0
	v_pk_mov_b32 v[48:49], 0, 0
	v_pk_mov_b32 v[50:51], 0, 0
	v_pk_mov_b32 v[52:53], 0, 0
	v_pk_mov_b32 v[54:55], 0, 0
	v_pk_mov_b32 v[56:57], 0, 0
	v_pk_mov_b32 v[58:59], 0, 0
	v_pk_mov_b32 v[60:61], 0, 0
	v_pk_mov_b32 v[62:63], 0, 0
	v_pk_mov_b32 v[64:65], 0, 0
	v_pk_mov_b32 v[66:67], 0, 0
	v_pk_mov_b32 v[68:69], 0, 0
	v_pk_mov_b32 v[70:71], 0, 0
	v_pk_mov_b32 v[72:73], 0, 0
	v_pk_mov_b32 v[74:75], 0, 0
	v_pk_mov_b32 v[76:77], 0, 0
	v_pk_mov_b32 v[78:79], 0, 0
	v_pk_mov_b32 v[80:81], 0, 0
	v_pk_mov_b32 v[82:83], 0, 0
	v_pk_mov_b32 v[84:85], 0, 0
	v_pk_mov_b32 v[86:87], 0, 0
	v_pk_mov_b32 v[88:89], 0, 0
	v_pk_mov_b32 v[90:91], 0, 0
	v_pk_mov_b32 v[92:93], 0, 0
	v_pk_mov_b32 v[94:95], 0, 0
	v_pk_mov_b32 v[96:97], 0, 0
	v_pk_mov_b32 v[98:99], 0, 0
	v_pk_mov_b32 v[100:101], 0, 0
	v_pk_mov_b32 v[102:103], 0, 0
	v_pk_mov_b32 v[104:105], 0, 0
	v_pk_mov_b32 v[106:107], 0, 0
	v_pk_mov_b32 v[108:109], 0, 0
	v_pk_mov_b32 v[110:111], 0, 0
	v_pk_mov_b32 v[112:113], 0, 0
	v_pk_mov_b32 v[114:115], 0, 0
	v_pk_mov_b32 v[116:117], 0, 0
	v_pk_mov_b32 v[118:119], 0, 0
	v_pk_mov_b32 v[120:121], 0, 0
	v_pk_mov_b32 v[122:123], 0, 0
	v_pk_mov_b32 v[124:125], 0, 0
	v_pk_mov_b32 v[126:127], 0, 0
	s_waitcnt lgkmcnt(0)
	s_cbranch_vccnz .LBB0_1654
	s_add_u32 s63, s26, 0x100
	s_addc_u32 s64, s27, 0
	s_mov_b32 s26, 0

; #define PG8_STAGE(bufoff, gbase, voff) do { _Pragma("unroll") for (int _i = 0; _i < 2; ++_i) \
;         __builtin_amdgcn_global_load_lds((const unsigned*)((const char*)(gbase) + (voff)[_i]), (LAS unsigned*)(lds + (bufoff) + ldsw + _i * 8192), 16, 0, 0); } while (0)
; #define PG8_WAIT_V(n) asm volatile("s_waitcnt vmcnt(" #n ")" ::: "memory")
; #define PG8_BAR __builtin_amdgcn_s_barrier()
; template <class Epi>
; __device__ __forceinline__ void gemm_phase(LAS unsigned char* lds, const Gemm g, const StaticOrder& S, const Epi& E) {
;     ...
;     f32x4 acc[2][2][4][2];
; #pragma unroll
;     for (int a = 0; a < 2; ++a)
; #pragma unroll
;         for (int b = 0; b < 2; ++b)
; #pragma unroll
;             for (int m = 0; m < 4; ++m)
; #pragma unroll
;                 for (int n = 0; n < 2; ++n) acc[a][b][m][n] = (f32x4){0.f, 0.f, 0.f, 0.f};
;     bf16x8 At[4][2], B0[2][2], B1[2][2];
;     const char* cA = (const char*)g.A + (size_t)cur.pm * tstepA + (size_t)cur.pn * g.a_pn_off * 2; const char* cB = (const char*)g.Bt + (size_t)cur.pn * tstepB;
;     PG8_STAGE(PG8_SB(0, 0), cB, voffB); PG8_STAGE(PG8_SA(0, 0), cA, voffA); PG8_STAGE(PG8_SB(0, 1), cB + hstepB, voffB); PG8_STAGE(PG8_SA(0, 1), cA + hstepA, voffA);
;     if (wr == 1) PG8_BAR;
;     PG8_WAIT_V(4); PG8_BAR;
;     PG8_STAGE(PG8_SB(1, 0), cB + kstep, voffB); PG8_STAGE(PG8_SA(1, 0), cA + kstep, voffA); PG8_STAGE(PG8_SB(1, 1), cB + hstepB + kstep, voffB);
;     PG8_WAIT_V(6); PG8_BAR;
;     for (;;) {
;         const bool has_next = S.next(ui + 1, nxt);
;         const char* nA = has_next ? (const char*)g.A + (size_t)nxt.pm * tstepA + (size_t)nxt.pn * g.a_pn_off * 2 : cA; const char* nB = has_next ? (const char*)g.Bt + (size_t)nxt.pn * tstepB : cB;
;         for (int t = 0; t < nt; t += 2) {
;             const bool last = (t == nt - 2);
;             const char* a1 = cA + (size_t)(t + 1) * kstep;
;             const char* a2 = last ? nA : cA + (size_t)(t + 2) * kstep; const char* b2 = last ? nB : cB + (size_t)(t + 2) * kstep;
.LBB0_1751:
	s_ashr_i32 s25, s24, 31
	s_lshl_b64 s[26:27], s[24:25], 19
	s_add_u32 s26, s68, s26
	s_addc_u32 s27, s69, s27
	s_ashr_i32 s23, s22, 31
	s_lshl_b64 s[28:29], s[22:23], 19
	s_add_u32 s28, s18, s28
	v_pk_mov_b32 v[0:1], 0, 0
	v_cmp_lt_i64_e64 s[12:13], s[12:13], v[172:173]
	s_addc_u32 s29, s19, s29
	s_and_b64 vcc, exec, s[8:9]
	v_pk_mov_b32 v[2:3], 0, 0
	v_pk_mov_b32 v[4:5], 0, 0
	v_pk_mov_b32 v[6:7], 0, 0
	v_pk_mov_b32 v[8:9], 0, 0
	v_pk_mov_b32 v[10:11], 0, 0
	v_pk_mov_b32 v[12:13], 0, 0
	v_pk_mov_b32 v[14:15], 0, 0
	v_pk_mov_b32 v[16:17], 0, 0
	v_pk_mov_b32 v[18:19], 0, 0
	v_pk_mov_b32 v[20:21], 0, 0
	v_pk_mov_b32 v[22:23], 0, 0
	v_pk_mov_b32 v[24:25], 0, 0
	v_pk_mov_b32 v[26:27], 0, 0
	v_pk_mov_b32 v[28:29], 0, 0
	v_pk_mov_b32 v[30:31], 0, 0
	v_pk_mov_b32 v[32:33], 0, 0
	v_pk_mov_b32 v[34:35], 0, 0
	v_pk_mov_b32 v[36:37], 0, 0
	v_pk_mov_b32 v[38:39], 0, 0
	v_pk_mov_b32 v[40:41], 0, 0
	v_pk_mov_b32 v[42:43], 0, 0
	v_pk_mov_b32 v[44:45], 0, 0
	v_pk_mov_b32 v[46:47], 0, 0
	v_pk_mov_b32 v[48:49], 0, 0
	v_pk_mov_b32 v[50:51], 0, 0
	v_pk_mov_b32 v[52:53], 0, 0
	v_pk_mov_b32 v[54:55], 0, 0
	v_pk_mov_b32 v[56:57], 0, 0
	v_pk_mov_b32 v[58:59], 0, 0
	v_pk_mov_b32 v[60:61], 0, 0
	v_pk_mov_b32 v[62:63], 0, 0
	v_pk_mov_b32 v[64:65], 0, 0
	v_pk_mov_b32 v[66:67], 0, 0
	v_pk_mov_b32 v[68:69], 0, 0
	v_pk_mov_b32 v[70:71], 0, 0
	v_pk_mov_b32 v[72:73], 0, 0
	v_pk_mov_b32 v[74:75], 0, 0
	v_pk_mov_b32 v[76:77], 0, 0
	v_pk_mov_b32 v[78:79], 0, 0
	v_pk_mov_b32 v[80:81], 0, 0
	v_pk_mov_b32 v[82:83], 0, 0
	v_pk_mov_b32 v[84:85], 0, 0
	v_pk_mov_b32 v[86:87], 0, 0
	v_pk_mov_b32 v[88:89], 0, 0
	v_pk_mov_b32 v[90:91], 0, 0
	v_pk_mov_b32 v[92:93], 0, 0
	v_pk_mov_b32 v[94:95], 0, 0
	v_pk_mov_b32 v[96:97], 0, 0
	v_pk_mov_b32 v[98:99], 0, 0
	v_pk_mov_b32 v[100:101], 0, 0
	v_pk_mov_b32 v[102:103], 0, 0
	v_pk_mov_b32 v[104:105], 0, 0
	v_pk_mov_b32 v[106:107], 0, 0
	v_pk_mov_b32 v[108:109], 0, 0
	v_pk_mov_b32 v[110:111], 0, 0
	v_pk_mov_b32 v[112:113], 0, 0
	v_pk_mov_b32 v[114:115], 0, 0
	v_pk_mov_b32 v[116:117], 0, 0
	v_pk_mov_b32 v[118:119], 0, 0
	v_pk_mov_b32 v[120:121], 0, 0
	v_pk_mov_b32 v[122:123], 0, 0
	v_pk_mov_b32 v[124:125], 0, 0
	v_pk_mov_b32 v[126:127], 0, 0
	s_waitcnt lgkmcnt(0)
	s_cbranch_vccnz .LBB0_1754
	s_and_b64 s[12:13], s[12:13], exec
	s_cselect_b32 s23, s27, s39
	s_cselect_b32 s25, s26, s38
	s_cselect_b32 s64, s29, s37
	s_cselect_b32 s65, s28, s36
	s_add_u32 s12, s38, 0x40080
	s_addc_u32 s13, s39, 0
	s_add_u32 s78, s36, 0x100
	s_addc_u32 s79, s37, 0
	s_mov_b32 s36, 0

; #define PG8_STAGE(bufoff, gbase, voff) do { _Pragma("unroll") for (int _i = 0; _i < 2; ++_i) \
;         __builtin_amdgcn_global_load_lds((const unsigned*)((const char*)(gbase) + (voff)[_i]), (LAS unsigned*)(lds + (bufoff) + ldsw + _i * 8192), 16, 0, 0); } while (0)
; #define PG8_WAIT_V(n) asm volatile("s_waitcnt vmcnt(" #n ")" ::: "memory")
; #define PG8_BAR __builtin_amdgcn_s_barrier()
; template <class Epi>
; __device__ __forceinline__ void gemm_phase(LAS unsigned char* lds, const Gemm g, const StaticOrder& S, const Epi& E) {
;     ...
;     f32x4 acc[2][2][4][2];
; #pragma unroll
;     for (int a = 0; a < 2; ++a)
; #pragma unroll
;         for (int b = 0; b < 2; ++b)
; #pragma unroll
;             for (int m = 0; m < 4; ++m)
; #pragma unroll
;                 for (int n = 0; n < 2; ++n) acc[a][b][m][n] = (f32x4){0.f, 0.f, 0.f, 0.f};
;     bf16x8 At[4][2], B0[2][2], B1[2][2];
;     const char* cA = (const char*)g.A + (size_t)cur.pm * tstepA + (size_t)cur.pn * g.a_pn_off * 2; const char* cB = (const char*)g.Bt + (size_t)cur.pn * tstepB;
;     PG8_STAGE(PG8_SB(0, 0), cB, voffB); PG8_STAGE(PG8_SA(0, 0), cA, voffA); PG8_STAGE(PG8_SB(0, 1), cB + hstepB, voffB); PG8_STAGE(PG8_SA(0, 1), cA + hstepA, voffA);
;     if (wr == 1) PG8_BAR;
;     PG8_WAIT_V(4); PG8_BAR;
;     PG8_STAGE(PG8_SB(1, 0), cB + kstep, voffB); PG8_STAGE(PG8_SA(1, 0), cA + kstep, voffA); PG8_STAGE(PG8_SB(1, 1), cB + hstepB + kstep, voffB);
;     PG8_WAIT_V(6); PG8_BAR;
;     for (;;) {
;         const bool has_next = S.next(ui + 1, nxt);
;         const char* nA = has_next ? (const char*)g.A + (size_t)nxt.pm * tstepA + (size_t)nxt.pn * g.a_pn_off * 2 : cA; const char* nB = has_next ? (const char*)g.Bt + (size_t)nxt.pn * tstepB : cB;
;         for (int t = 0; t < nt; t += 2) {
;             const bool last = (t == nt - 2);
;             const char* a1 = cA + (size_t)(t + 1) * kstep;
;             const char* a2 = last ? nA : cA + (size_t)(t + 2) * kstep; const char* b2 = last ? nB : cB + (size_t)(t + 2) * kstep;
.LBB0_1855:
	s_ashr_i32 s23, s22, 31
	s_lshl_b64 s[24:25], s[22:23], 19
	s_add_u32 s24, s70, s24
	s_addc_u32 s25, s71, s25
	s_ashr_i32 s21, s20, 31
	s_lshl_b64 s[26:27], s[20:21], 19
	s_add_u32 s26, s12, s26
	v_pk_mov_b32 v[0:1], 0, 0
	v_cmp_lt_i64_e64 s[8:9], s[8:9], v[140:141]
	s_addc_u32 s27, s13, s27
	s_andn2_b64 vcc, exec, s[18:19]
	v_pk_mov_b32 v[2:3], 0, 0
	v_pk_mov_b32 v[4:5], 0, 0
	v_pk_mov_b32 v[6:7], 0, 0
	v_pk_mov_b32 v[8:9], 0, 0
	v_pk_mov_b32 v[10:11], 0, 0
	v_pk_mov_b32 v[12:13], 0, 0
	v_pk_mov_b32 v[14:15], 0, 0
	v_pk_mov_b32 v[16:17], 0, 0
	v_pk_mov_b32 v[18:19], 0, 0
	v_pk_mov_b32 v[20:21], 0, 0
	v_pk_mov_b32 v[22:23], 0, 0
	v_pk_mov_b32 v[24:25], 0, 0
	v_pk_mov_b32 v[26:27], 0, 0
	v_pk_mov_b32 v[28:29], 0, 0
	v_pk_mov_b32 v[30:31], 0, 0
	v_pk_mov_b32 v[32:33], 0, 0
	v_pk_mov_b32 v[34:35], 0, 0
	v_pk_mov_b32 v[36:37], 0, 0
	v_pk_mov_b32 v[38:39], 0, 0
	v_pk_mov_b32 v[40:41], 0, 0
	v_pk_mov_b32 v[42:43], 0, 0
	v_pk_mov_b32 v[44:45], 0, 0
	v_pk_mov_b32 v[46:47], 0, 0
	v_pk_mov_b32 v[48:49], 0, 0
	v_pk_mov_b32 v[50:51], 0, 0
	v_pk_mov_b32 v[52:53], 0, 0
	v_pk_mov_b32 v[54:55], 0, 0
	v_pk_mov_b32 v[56:57], 0, 0
	v_pk_mov_b32 v[58:59], 0, 0
	v_pk_mov_b32 v[60:61], 0, 0
	v_pk_mov_b32 v[62:63], 0, 0
	v_pk_mov_b32 v[64:65], 0, 0
	v_pk_mov_b32 v[66:67], 0, 0
	v_pk_mov_b32 v[68:69], 0, 0
	v_pk_mov_b32 v[70:71], 0, 0
	v_pk_mov_b32 v[72:73], 0, 0
	v_pk_mov_b32 v[74:75], 0, 0
	v_pk_mov_b32 v[76:77], 0, 0
	v_pk_mov_b32 v[78:79], 0, 0
	v_pk_mov_b32 v[80:81], 0, 0
	v_pk_mov_b32 v[82:83], 0, 0
	v_pk_mov_b32 v[84:85], 0, 0
	v_pk_mov_b32 v[86:87], 0, 0
	v_pk_mov_b32 v[88:89], 0, 0
	v_pk_mov_b32 v[90:91], 0, 0
	v_pk_mov_b32 v[92:93], 0, 0
	v_pk_mov_b32 v[94:95], 0, 0
	v_pk_mov_b32 v[96:97], 0, 0
	v_pk_mov_b32 v[98:99], 0, 0
	v_pk_mov_b32 v[100:101], 0, 0
	v_pk_mov_b32 v[102:103], 0, 0
	v_pk_mov_b32 v[104:105], 0, 0
	v_pk_mov_b32 v[106:107], 0, 0
	v_pk_mov_b32 v[108:109], 0, 0
	v_pk_mov_b32 v[110:111], 0, 0
	v_pk_mov_b32 v[112:113], 0, 0
	v_pk_mov_b32 v[114:115], 0, 0
	v_pk_mov_b32 v[116:117], 0, 0
	v_pk_mov_b32 v[118:119], 0, 0
	v_pk_mov_b32 v[120:121], 0, 0
	v_pk_mov_b32 v[122:123], 0, 0
	v_pk_mov_b32 v[124:125], 0, 0
	v_pk_mov_b32 v[126:127], 0, 0
	s_cbranch_vccnz .LBB0_1858
	s_and_b64 s[8:9], s[8:9], exec
	s_cselect_b32 s21, s25, s37
	s_cselect_b32 s23, s24, s36
	s_cselect_b32 s65, s27, s31
	s_cselect_b32 s77, s26, s30
	s_add_u32 s8, s36, 0x40080
	s_addc_u32 s9, s37, 0
	s_add_u32 s78, s30, 0x100
	s_addc_u32 s79, s31, 0
	s_mov_b32 s30, 0

; #define PG8_STAGE(bufoff, gbase, voff) do { _Pragma("unroll") for (int _i = 0; _i < 2; ++_i) \
;         __builtin_amdgcn_global_load_lds((const unsigned*)((const char*)(gbase) + (voff)[_i]), (LAS unsigned*)(lds + (bufoff) + ldsw + _i * 8192), 16, 0, 0); } while (0)
; #define PG8_WAIT_V(n) asm volatile("s_waitcnt vmcnt(" #n ")" ::: "memory")
; #define PG8_BAR __builtin_amdgcn_s_barrier()
; template <class Epi>
; __device__ __forceinline__ void gemm_phase(LAS unsigned char* lds, const Gemm g, const StaticOrder& S, const Epi& E) {
;     ...
;     f32x4 acc[2][2][4][2];
; #pragma unroll
;     for (int a = 0; a < 2; ++a)
; #pragma unroll
;         for (int b = 0; b < 2; ++b)
; #pragma unroll
;             for (int m = 0; m < 4; ++m)
; #pragma unroll
;                 for (int n = 0; n < 2; ++n) acc[a][b][m][n] = (f32x4){0.f, 0.f, 0.f, 0.f};
;     bf16x8 At[4][2], B0[2][2], B1[2][2];
;     const char* cA = (const char*)g.A + (size_t)cur.pm * tstepA + (size_t)cur.pn * g.a_pn_off * 2; const char* cB = (const char*)g.Bt + (size_t)cur.pn * tstepB;
;     PG8_STAGE(PG8_SB(0, 0), cB, voffB); PG8_STAGE(PG8_SA(0, 0), cA, voffA); PG8_STAGE(PG8_SB(0, 1), cB + hstepB, voffB); PG8_STAGE(PG8_SA(0, 1), cA + hstepA, voffA);
;     if (wr == 1) PG8_BAR;
;     PG8_WAIT_V(4); PG8_BAR;
;     PG8_STAGE(PG8_SB(1, 0), cB + kstep, voffB); PG8_STAGE(PG8_SA(1, 0), cA + kstep, voffA); PG8_STAGE(PG8_SB(1, 1), cB + hstepB + kstep, voffB);
;     PG8_WAIT_V(6); PG8_BAR;
;     for (;;) {
;         const bool has_next = S.next(ui + 1, nxt);
;         const char* nA = has_next ? (const char*)g.A + (size_t)nxt.pm * tstepA + (size_t)nxt.pn * g.a_pn_off * 2 : cA; const char* nB = has_next ? (const char*)g.Bt + (size_t)nxt.pn * tstepB : cB;
;         for (int t = 0; t < nt; t += 2) {
;             const bool last = (t == nt - 2);
;             const char* a1 = cA + (size_t)(t + 1) * kstep;
;             const char* a2 = last ? nA : cA + (size_t)(t + 2) * kstep; const char* b2 = last ? nB : cB + (size_t)(t + 2) * kstep;
.LBB0_1893:
	s_ashr_i32 s63, s62, 31
	s_lshl_b64 s[14:15], s[62:63], 19
	s_add_u32 s76, s36, s14
	s_addc_u32 s77, s37, s15
	s_ashr_i32 s61, s60, 31
	s_lshl_b64 s[14:15], s[60:61], 19
	s_add_u32 s78, s70, s14
	v_pk_mov_b32 v[0:1], 0, 0
	v_cmp_lt_i64_e64 s[8:9], s[8:9], v[140:141]
	s_addc_u32 s79, s71, s15
	s_andn2_b64 vcc, exec, s[42:43]
	v_pk_mov_b32 v[2:3], 0, 0
	v_pk_mov_b32 v[4:5], 0, 0
	v_pk_mov_b32 v[6:7], 0, 0
	v_pk_mov_b32 v[8:9], 0, 0
	v_pk_mov_b32 v[10:11], 0, 0
	v_pk_mov_b32 v[12:13], 0, 0
	v_pk_mov_b32 v[14:15], 0, 0
	v_pk_mov_b32 v[16:17], 0, 0
	v_pk_mov_b32 v[18:19], 0, 0
	v_pk_mov_b32 v[20:21], 0, 0
	v_pk_mov_b32 v[22:23], 0, 0
	v_pk_mov_b32 v[24:25], 0, 0
	v_pk_mov_b32 v[26:27], 0, 0
	v_pk_mov_b32 v[28:29], 0, 0
	v_pk_mov_b32 v[30:31], 0, 0
	v_pk_mov_b32 v[32:33], 0, 0
	v_pk_mov_b32 v[34:35], 0, 0
	v_pk_mov_b32 v[36:37], 0, 0
	v_pk_mov_b32 v[38:39], 0, 0
	v_pk_mov_b32 v[40:41], 0, 0
	v_pk_mov_b32 v[42:43], 0, 0
	v_pk_mov_b32 v[44:45], 0, 0
	v_pk_mov_b32 v[46:47], 0, 0
	v_pk_mov_b32 v[48:49], 0, 0
	v_pk_mov_b32 v[50:51], 0, 0
	v_pk_mov_b32 v[52:53], 0, 0
	v_pk_mov_b32 v[54:55], 0, 0
	v_pk_mov_b32 v[56:57], 0, 0
	v_pk_mov_b32 v[58:59], 0, 0
	v_pk_mov_b32 v[60:61], 0, 0
	v_pk_mov_b32 v[62:63], 0, 0
	v_pk_mov_b32 v[64:65], 0, 0
	v_pk_mov_b32 v[66:67], 0, 0
	v_pk_mov_b32 v[68:69], 0, 0
	v_pk_mov_b32 v[70:71], 0, 0
	v_pk_mov_b32 v[72:73], 0, 0
	v_pk_mov_b32 v[74:75], 0, 0
	v_pk_mov_b32 v[76:77], 0, 0
	v_pk_mov_b32 v[78:79], 0, 0
	v_pk_mov_b32 v[80:81], 0, 0
	v_pk_mov_b32 v[82:83], 0, 0
	v_pk_mov_b32 v[84:85], 0, 0
	v_pk_mov_b32 v[86:87], 0, 0
	v_pk_mov_b32 v[88:89], 0, 0
	v_pk_mov_b32 v[90:91], 0, 0
	v_pk_mov_b32 v[92:93], 0, 0
	v_pk_mov_b32 v[94:95], 0, 0
	v_pk_mov_b32 v[96:97], 0, 0
	v_pk_mov_b32 v[98:99], 0, 0
	v_pk_mov_b32 v[100:101], 0, 0
	v_pk_mov_b32 v[102:103], 0, 0
	v_pk_mov_b32 v[104:105], 0, 0
	v_pk_mov_b32 v[106:107], 0, 0
	v_pk_mov_b32 v[108:109], 0, 0
	v_pk_mov_b32 v[110:111], 0, 0
	v_pk_mov_b32 v[112:113], 0, 0
	v_pk_mov_b32 v[114:115], 0, 0
	v_pk_mov_b32 v[116:117], 0, 0
	v_pk_mov_b32 v[118:119], 0, 0
	v_pk_mov_b32 v[120:121], 0, 0
	v_pk_mov_b32 v[122:123], 0, 0
	v_pk_mov_b32 v[124:125], 0, 0
	v_pk_mov_b32 v[126:127], 0, 0
	s_cbranch_vccnz .LBB0_1886
	s_and_b64 s[8:9], s[8:9], exec
	s_cselect_b32 s14, s77, s13
	s_cselect_b32 s15, s76, s12
	s_cselect_b32 s17, s79, s11
	s_cselect_b32 s18, s78, s10
	s_add_u32 s8, s12, 0x40080
	s_addc_u32 s9, s13, 0
	s_add_u32 s19, s10, 0x100
	s_addc_u32 s20, s11, 0
	s_mov_b32 s10, 0

; #define PG8_STAGE(bufoff, gbase, voff) do { _Pragma("unroll") for (int _i = 0; _i < 2; ++_i) \
;         __builtin_amdgcn_global_load_lds((const unsigned*)((const char*)(gbase) + (voff)[_i]), (LAS unsigned*)(lds + (bufoff) + ldsw + _i * 8192), 16, 0, 0); } while (0)
; #define PG8_WAIT_V(n) asm volatile("s_waitcnt vmcnt(" #n ")" ::: "memory")
; #define PG8_BAR __builtin_amdgcn_s_barrier()
; template <class Epi>
; __device__ __forceinline__ void gemm_phase(LAS unsigned char* lds, const Gemm g, const StaticOrder& S, const Epi& E) {
;     ...
;     f32x4 acc[2][2][4][2];
; #pragma unroll
;     for (int a = 0; a < 2; ++a)
; #pragma unroll
;         for (int b = 0; b < 2; ++b)
; #pragma unroll
;             for (int m = 0; m < 4; ++m)
; #pragma unroll
;                 for (int n = 0; n < 2; ++n) acc[a][b][m][n] = (f32x4){0.f, 0.f, 0.f, 0.f};
;     bf16x8 At[4][2], B0[2][2], B1[2][2];
;     const char* cA = (const char*)g.A + (size_t)cur.pm * tstepA + (size_t)cur.pn * g.a_pn_off * 2; const char* cB = (const char*)g.Bt + (size_t)cur.pn * tstepB;
;     PG8_STAGE(PG8_SB(0, 0), cB, voffB); PG8_STAGE(PG8_SA(0, 0), cA, voffA); PG8_STAGE(PG8_SB(0, 1), cB + hstepB, voffB); PG8_STAGE(PG8_SA(0, 1), cA + hstepA, voffA);
;     if (wr == 1) PG8_BAR;
;     PG8_WAIT_V(4); PG8_BAR;
;     PG8_STAGE(PG8_SB(1, 0), cB + kstep, voffB); PG8_STAGE(PG8_SA(1, 0), cA + kstep, voffA); PG8_STAGE(PG8_SB(1, 1), cB + hstepB + kstep, voffB);
;     PG8_WAIT_V(6); PG8_BAR;
;     for (;;) {
;         const bool has_next = S.next(ui + 1, nxt);
;         const char* nA = has_next ? (const char*)g.A + (size_t)nxt.pm * tstepA + (size_t)nxt.pn * g.a_pn_off * 2 : cA; const char* nB = has_next ? (const char*)g.Bt + (size_t)nxt.pn * tstepB : cB;
;         for (int t = 0; t < nt; t += 2) {
;             const bool last = (t == nt - 2);
;             const char* a1 = cA + (size_t)(t + 1) * kstep;
;             const char* a2 = last ? nA : cA + (size_t)(t + 2) * kstep; const char* b2 = last ? nB : cB + (size_t)(t + 2) * kstep;
.LBB0_2294:
	s_ashr_i32 s23, s22, 31
	s_lshl_b64 s[24:25], s[22:23], 19
	s_add_u32 s24, s70, s24
	s_addc_u32 s25, s71, s25
	s_ashr_i32 s21, s20, 31
	s_lshl_b64 s[26:27], s[20:21], 19
	s_add_u32 s26, s16, s26
	v_pk_mov_b32 v[0:1], 0, 0
	v_cmp_lt_i64_e64 s[12:13], s[12:13], v[188:189]
	s_addc_u32 s27, s17, s27
	s_and_b64 vcc, exec, s[8:9]
	v_pk_mov_b32 v[2:3], 0, 0
	v_pk_mov_b32 v[4:5], 0, 0
	v_pk_mov_b32 v[6:7], 0, 0
	v_pk_mov_b32 v[8:9], 0, 0
	v_pk_mov_b32 v[10:11], 0, 0
	v_pk_mov_b32 v[12:13], 0, 0
	v_pk_mov_b32 v[14:15], 0, 0
	v_pk_mov_b32 v[16:17], 0, 0
	v_pk_mov_b32 v[18:19], 0, 0
	v_pk_mov_b32 v[20:21], 0, 0
	v_pk_mov_b32 v[22:23], 0, 0
	v_pk_mov_b32 v[24:25], 0, 0
	v_pk_mov_b32 v[26:27], 0, 0
	v_pk_mov_b32 v[28:29], 0, 0
	v_pk_mov_b32 v[30:31], 0, 0
	v_pk_mov_b32 v[32:33], 0, 0
	v_pk_mov_b32 v[34:35], 0, 0
	v_pk_mov_b32 v[36:37], 0, 0
	v_pk_mov_b32 v[38:39], 0, 0
	v_pk_mov_b32 v[40:41], 0, 0
	v_pk_mov_b32 v[42:43], 0, 0
	v_pk_mov_b32 v[44:45], 0, 0
	v_pk_mov_b32 v[46:47], 0, 0
	v_pk_mov_b32 v[48:49], 0, 0
	v_pk_mov_b32 v[50:51], 0, 0
	v_pk_mov_b32 v[52:53], 0, 0
	v_pk_mov_b32 v[54:55], 0, 0
	v_pk_mov_b32 v[56:57], 0, 0
	v_pk_mov_b32 v[58:59], 0, 0
	v_pk_mov_b32 v[60:61], 0, 0
	v_pk_mov_b32 v[62:63], 0, 0
	v_pk_mov_b32 v[64:65], 0, 0
	v_pk_mov_b32 v[66:67], 0, 0
	v_pk_mov_b32 v[68:69], 0, 0
	v_pk_mov_b32 v[70:71], 0, 0
	v_pk_mov_b32 v[72:73], 0, 0
	v_pk_mov_b32 v[74:75], 0, 0
	v_pk_mov_b32 v[76:77], 0, 0
	v_pk_mov_b32 v[78:79], 0, 0
	v_pk_mov_b32 v[80:81], 0, 0
	v_pk_mov_b32 v[82:83], 0, 0
	v_pk_mov_b32 v[84:85], 0, 0
	v_pk_mov_b32 v[86:87], 0, 0
	v_pk_mov_b32 v[88:89], 0, 0
	v_pk_mov_b32 v[90:91], 0, 0
	v_pk_mov_b32 v[92:93], 0, 0
	v_pk_mov_b32 v[94:95], 0, 0
	v_pk_mov_b32 v[96:97], 0, 0
	v_pk_mov_b32 v[98:99], 0, 0
	v_pk_mov_b32 v[100:101], 0, 0
	v_pk_mov_b32 v[102:103], 0, 0
	v_pk_mov_b32 v[104:105], 0, 0
	v_pk_mov_b32 v[106:107], 0, 0
	v_pk_mov_b32 v[108:109], 0, 0
	v_pk_mov_b32 v[110:111], 0, 0
	v_pk_mov_b32 v[112:113], 0, 0
	v_pk_mov_b32 v[114:115], 0, 0
	v_pk_mov_b32 v[116:117], 0, 0
	v_pk_mov_b32 v[118:119], 0, 0
	v_pk_mov_b32 v[120:121], 0, 0
	v_pk_mov_b32 v[122:123], 0, 0
	v_pk_mov_b32 v[124:125], 0, 0
	v_pk_mov_b32 v[126:127], 0, 0
	s_waitcnt lgkmcnt(0)
	s_cbranch_vccnz .LBB0_2297
	s_and_b64 s[12:13], s[12:13], exec
	s_cselect_b32 s21, s25, s37
	s_cselect_b32 s23, s24, s36
	s_cselect_b32 s63, s27, s35
	s_cselect_b32 s64, s26, s34
	s_add_u32 s12, s36, 0x40080
	s_addc_u32 s13, s37, 0
	s_add_u32 s65, s34, 0x100
	s_addc_u32 s76, s35, 0
	s_mov_b32 s34, 0

; #define PG8_STAGE(bufoff, gbase, voff) do { _Pragma("unroll") for (int _i = 0; _i < 2; ++_i) \
;         __builtin_amdgcn_global_load_lds((const unsigned*)((const char*)(gbase) + (voff)[_i]), (LAS unsigned*)(lds + (bufoff) + ldsw + _i * 8192), 16, 0, 0); } while (0)
; #define PG8_WAIT_V(n) asm volatile("s_waitcnt vmcnt(" #n ")" ::: "memory")
; #define PG8_BAR __builtin_amdgcn_s_barrier()
; template <class Epi>
; __device__ __forceinline__ void gemm_phase(LAS unsigned char* lds, const Gemm g, const StaticOrder& S, const Epi& E) {
;     ...
;     f32x4 acc[2][2][4][2];
; #pragma unroll
;     for (int a = 0; a < 2; ++a)
; #pragma unroll
;         for (int b = 0; b < 2; ++b)
; #pragma unroll
;             for (int m = 0; m < 4; ++m)
; #pragma unroll
;                 for (int n = 0; n < 2; ++n) acc[a][b][m][n] = (f32x4){0.f, 0.f, 0.f, 0.f};
;     bf16x8 At[4][2], B0[2][2], B1[2][2];
;     const char* cA = (const char*)g.A + (size_t)cur.pm * tstepA + (size_t)cur.pn * g.a_pn_off * 2; const char* cB = (const char*)g.Bt + (size_t)cur.pn * tstepB;
;     PG8_STAGE(PG8_SB(0, 0), cB, voffB); PG8_STAGE(PG8_SA(0, 0), cA, voffA); PG8_STAGE(PG8_SB(0, 1), cB + hstepB, voffB); PG8_STAGE(PG8_SA(0, 1), cA + hstepA, voffA);
;     if (wr == 1) PG8_BAR;
;     PG8_WAIT_V(4); PG8_BAR;
;     PG8_STAGE(PG8_SB(1, 0), cB + kstep, voffB); PG8_STAGE(PG8_SA(1, 0), cA + kstep, voffA); PG8_STAGE(PG8_SB(1, 1), cB + hstepB + kstep, voffB);
;     PG8_WAIT_V(6); PG8_BAR;
;     for (;;) {
;         const bool has_next = S.next(ui + 1, nxt);
;         const char* nA = has_next ? (const char*)g.A + (size_t)nxt.pm * tstepA + (size_t)nxt.pn * g.a_pn_off * 2 : cA; const char* nB = has_next ? (const char*)g.Bt + (size_t)nxt.pn * tstepB : cB;
;         for (int t = 0; t < nt; t += 2) {
;             const bool last = (t == nt - 2);
;             const char* a1 = cA + (size_t)(t + 1) * kstep;
;             const char* a2 = last ? nA : cA + (size_t)(t + 2) * kstep; const char* b2 = last ? nB : cB + (size_t)(t + 2) * kstep;
.LBB0_2409:
	s_ashr_i32 s19, s18, 31
	s_lshl_b64 s[20:21], s[18:19], 19
	s_add_u32 s20, s68, s20
	s_addc_u32 s21, s69, s21
	s_ashr_i32 s17, s16, 31
	s_lshl_b64 s[22:23], s[16:17], 19
	s_add_u32 s22, s31, s22
	v_pk_mov_b32 v[0:1], 0, 0
	v_cmp_lt_i64_e64 s[8:9], s[8:9], v[140:141]
	s_addc_u32 s23, s34, s23
	s_andn2_b64 vcc, exec, s[14:15]
	v_pk_mov_b32 v[2:3], 0, 0
	v_pk_mov_b32 v[4:5], 0, 0
	v_pk_mov_b32 v[6:7], 0, 0
	v_pk_mov_b32 v[8:9], 0, 0
	v_pk_mov_b32 v[10:11], 0, 0
	v_pk_mov_b32 v[12:13], 0, 0
	v_pk_mov_b32 v[14:15], 0, 0
	v_pk_mov_b32 v[16:17], 0, 0
	v_pk_mov_b32 v[18:19], 0, 0
	v_pk_mov_b32 v[20:21], 0, 0
	v_pk_mov_b32 v[22:23], 0, 0
	v_pk_mov_b32 v[24:25], 0, 0
	v_pk_mov_b32 v[26:27], 0, 0
	v_pk_mov_b32 v[28:29], 0, 0
	v_pk_mov_b32 v[30:31], 0, 0
	v_pk_mov_b32 v[32:33], 0, 0
	v_pk_mov_b32 v[34:35], 0, 0
	v_pk_mov_b32 v[36:37], 0, 0
	v_pk_mov_b32 v[38:39], 0, 0
	v_pk_mov_b32 v[40:41], 0, 0
	v_pk_mov_b32 v[42:43], 0, 0
	v_pk_mov_b32 v[44:45], 0, 0
	v_pk_mov_b32 v[46:47], 0, 0
	v_pk_mov_b32 v[48:49], 0, 0
	v_pk_mov_b32 v[50:51], 0, 0
	v_pk_mov_b32 v[52:53], 0, 0
	v_pk_mov_b32 v[54:55], 0, 0
	v_pk_mov_b32 v[56:57], 0, 0
	v_pk_mov_b32 v[58:59], 0, 0
	v_pk_mov_b32 v[60:61], 0, 0
	v_pk_mov_b32 v[62:63], 0, 0
	v_pk_mov_b32 v[64:65], 0, 0
	v_pk_mov_b32 v[66:67], 0, 0
	v_pk_mov_b32 v[68:69], 0, 0
	v_pk_mov_b32 v[70:71], 0, 0
	v_pk_mov_b32 v[72:73], 0, 0
	v_pk_mov_b32 v[74:75], 0, 0
	v_pk_mov_b32 v[76:77], 0, 0
	v_pk_mov_b32 v[78:79], 0, 0
	v_pk_mov_b32 v[80:81], 0, 0
	v_pk_mov_b32 v[82:83], 0, 0
	v_pk_mov_b32 v[84:85], 0, 0
	v_pk_mov_b32 v[86:87], 0, 0
	v_pk_mov_b32 v[88:89], 0, 0
	v_pk_mov_b32 v[90:91], 0, 0
	v_pk_mov_b32 v[92:93], 0, 0
	v_pk_mov_b32 v[94:95], 0, 0
	v_pk_mov_b32 v[96:97], 0, 0
	v_pk_mov_b32 v[98:99], 0, 0
	v_pk_mov_b32 v[100:101], 0, 0
	v_pk_mov_b32 v[102:103], 0, 0
	v_pk_mov_b32 v[104:105], 0, 0
	v_pk_mov_b32 v[106:107], 0, 0
	v_pk_mov_b32 v[108:109], 0, 0
	v_pk_mov_b32 v[110:111], 0, 0
	v_pk_mov_b32 v[112:113], 0, 0
	v_pk_mov_b32 v[114:115], 0, 0
	v_pk_mov_b32 v[116:117], 0, 0
	v_pk_mov_b32 v[118:119], 0, 0
	v_pk_mov_b32 v[120:121], 0, 0
	v_pk_mov_b32 v[122:123], 0, 0
	v_pk_mov_b32 v[124:125], 0, 0
	v_pk_mov_b32 v[126:127], 0, 0
	s_cbranch_vccnz .LBB0_2402
	s_and_b64 s[8:9], s[8:9], exec
	s_cselect_b32 s17, s21, s29
	s_cselect_b32 s19, s20, s28
	s_cselect_b32 s63, s23, s27
	s_cselect_b32 s64, s22, s26
	s_add_u32 s8, s28, 0x40080
	s_addc_u32 s9, s29, 0
	s_add_u32 s65, s26, 0x100
	s_addc_u32 s76, s27, 0
	s_mov_b32 s26, 0

; #define PG8_STAGE(bufoff, gbase, voff) do { _Pragma("unroll") for (int _i = 0; _i < 2; ++_i) \
;         __builtin_amdgcn_global_load_lds((const unsigned*)((const char*)(gbase) + (voff)[_i]), (LAS unsigned*)(lds + (bufoff) + ldsw + _i * 8192), 16, 0, 0); } while (0)
; #define PG8_WAIT_V(n) asm volatile("s_waitcnt vmcnt(" #n ")" ::: "memory")
; #define PG8_BAR __builtin_amdgcn_s_barrier()
; template <class Epi>
; __device__ __forceinline__ void gemm_phase(LAS unsigned char* lds, const Gemm g, const StaticOrder& S, const Epi& E) {
;     ...
;     f32x4 acc[2][2][4][2];
; #pragma unroll
;     for (int a = 0; a < 2; ++a)
; #pragma unroll
;         for (int b = 0; b < 2; ++b)
; #pragma unroll
;             for (int m = 0; m < 4; ++m)
; #pragma unroll
;                 for (int n = 0; n < 2; ++n) acc[a][b][m][n] = (f32x4){0.f, 0.f, 0.f, 0.f};
;     bf16x8 At[4][2], B0[2][2], B1[2][2];
;     const char* cA = (const char*)g.A + (size_t)cur.pm * tstepA + (size_t)cur.pn * g.a_pn_off * 2; const char* cB = (const char*)g.Bt + (size_t)cur.pn * tstepB;
;     PG8_STAGE(PG8_SB(0, 0), cB, voffB); PG8_STAGE(PG8_SA(0, 0), cA, voffA); PG8_STAGE(PG8_SB(0, 1), cB + hstepB, voffB); PG8_STAGE(PG8_SA(0, 1), cA + hstepA, voffA);
;     if (wr == 1) PG8_BAR;
;     PG8_WAIT_V(4); PG8_BAR;
;     PG8_STAGE(PG8_SB(1, 0), cB + kstep, voffB); PG8_STAGE(PG8_SA(1, 0), cA + kstep, voffA); PG8_STAGE(PG8_SB(1, 1), cB + hstepB + kstep, voffB);
;     PG8_WAIT_V(6); PG8_BAR;
;     for (;;) {
;         const bool has_next = S.next(ui + 1, nxt);
;         const char* nA = has_next ? (const char*)g.A + (size_t)nxt.pm * tstepA + (size_t)nxt.pn * g.a_pn_off * 2 : cA; const char* nB = has_next ? (const char*)g.Bt + (size_t)nxt.pn * tstepB : cB;
;         for (int t = 0; t < nt; t += 2) {
;             const bool last = (t == nt - 2);
;             const char* a1 = cA + (size_t)(t + 1) * kstep;
;             const char* a2 = last ? nA : cA + (size_t)(t + 2) * kstep; const char* b2 = last ? nB : cB + (size_t)(t + 2) * kstep;
.LBB0_2431:
	s_ashr_i32 s23, s22, 31
	s_lshl_b64 s[24:25], s[22:23], 17
	s_add_u32 s24, s14, s24
	s_addc_u32 s25, s15, s25
	s_ashr_i32 s21, s20, 31
	s_lshl_b64 s[26:27], s[20:21], 17
	s_add_u32 s26, s12, s26
	v_pk_mov_b32 v[0:1], 0, 0
	v_cmp_lt_i64_e64 s[10:11], s[10:11], v[140:141]
	s_addc_u32 s27, s13, s27
	s_and_b64 vcc, exec, s[6:7]
	v_pk_mov_b32 v[2:3], 0, 0
	v_pk_mov_b32 v[4:5], 0, 0
	v_pk_mov_b32 v[6:7], 0, 0
	v_pk_mov_b32 v[8:9], 0, 0
	v_pk_mov_b32 v[10:11], 0, 0
	v_pk_mov_b32 v[12:13], 0, 0
	v_pk_mov_b32 v[14:15], 0, 0
	v_pk_mov_b32 v[16:17], 0, 0
	v_pk_mov_b32 v[18:19], 0, 0
	v_pk_mov_b32 v[20:21], 0, 0
	v_pk_mov_b32 v[22:23], 0, 0
	v_pk_mov_b32 v[24:25], 0, 0
	v_pk_mov_b32 v[26:27], 0, 0
	v_pk_mov_b32 v[28:29], 0, 0
	v_pk_mov_b32 v[30:31], 0, 0
	v_pk_mov_b32 v[32:33], 0, 0
	v_pk_mov_b32 v[34:35], 0, 0
	v_pk_mov_b32 v[36:37], 0, 0
	v_pk_mov_b32 v[38:39], 0, 0
	v_pk_mov_b32 v[40:41], 0, 0
	v_pk_mov_b32 v[42:43], 0, 0
	v_pk_mov_b32 v[44:45], 0, 0
	v_pk_mov_b32 v[46:47], 0, 0
	v_pk_mov_b32 v[48:49], 0, 0
	v_pk_mov_b32 v[50:51], 0, 0
	v_pk_mov_b32 v[52:53], 0, 0
	v_pk_mov_b32 v[54:55], 0, 0
	v_pk_mov_b32 v[56:57], 0, 0
	v_pk_mov_b32 v[58:59], 0, 0
	v_pk_mov_b32 v[60:61], 0, 0
	v_pk_mov_b32 v[62:63], 0, 0
	v_pk_mov_b32 v[64:65], 0, 0
	v_pk_mov_b32 v[66:67], 0, 0
	v_pk_mov_b32 v[68:69], 0, 0
	v_pk_mov_b32 v[70:71], 0, 0
	v_pk_mov_b32 v[72:73], 0, 0
	v_pk_mov_b32 v[74:75], 0, 0
	v_pk_mov_b32 v[76:77], 0, 0
	v_pk_mov_b32 v[78:79], 0, 0
	v_pk_mov_b32 v[80:81], 0, 0
	v_pk_mov_b32 v[82:83], 0, 0
	v_pk_mov_b32 v[84:85], 0, 0
	v_pk_mov_b32 v[86:87], 0, 0
	v_pk_mov_b32 v[88:89], 0, 0
	v_pk_mov_b32 v[90:91], 0, 0
	v_pk_mov_b32 v[92:93], 0, 0
	v_pk_mov_b32 v[94:95], 0, 0
	v_pk_mov_b32 v[96:97], 0, 0
	v_pk_mov_b32 v[98:99], 0, 0
	v_pk_mov_b32 v[100:101], 0, 0
	v_pk_mov_b32 v[102:103], 0, 0
	v_pk_mov_b32 v[104:105], 0, 0
	v_pk_mov_b32 v[106:107], 0, 0
	v_pk_mov_b32 v[108:109], 0, 0
	v_pk_mov_b32 v[110:111], 0, 0
	v_pk_mov_b32 v[112:113], 0, 0
	v_pk_mov_b32 v[114:115], 0, 0
	v_pk_mov_b32 v[116:117], 0, 0
	v_pk_mov_b32 v[118:119], 0, 0
	v_pk_mov_b32 v[120:121], 0, 0
	v_pk_mov_b32 v[122:123], 0, 0
	v_pk_mov_b32 v[124:125], 0, 0
	v_pk_mov_b32 v[126:127], 0, 0
	s_cbranch_vccnz .LBB0_2424
	s_and_b64 s[10:11], s[10:11], exec
	s_cselect_b32 s21, s25, s31
	s_cselect_b32 s23, s24, s30
	s_cselect_b32 s62, s27, s29
	s_cselect_b32 s63, s26, s28
	s_add_u32 s10, s30, 0x10080
	s_addc_u32 s11, s31, 0
	s_add_u32 s64, s28, 0x100
	s_addc_u32 s65, s29, 0
	s_mov_b32 s28, 0

; #define PG8_STAGE(bufoff, gbase, voff) do { _Pragma("unroll") for (int _i = 0; _i < 2; ++_i) \
;         __builtin_amdgcn_global_load_lds((const unsigned*)((const char*)(gbase) + (voff)[_i]), (LAS unsigned*)(lds + (bufoff) + ldsw + _i * 8192), 16, 0, 0); } while (0)
; #define PG8_WAIT_V(n) asm volatile("s_waitcnt vmcnt(" #n ")" ::: "memory")
; #define PG8_BAR __builtin_amdgcn_s_barrier()
; template <class Epi>
; __device__ __forceinline__ void gemm_phase(LAS unsigned char* lds, const Gemm g, const StaticOrder& S, const Epi& E) {
;     ...
;     f32x4 acc[2][2][4][2];
; #pragma unroll
;     for (int a = 0; a < 2; ++a)
; #pragma unroll
;         for (int b = 0; b < 2; ++b)
; #pragma unroll
;             for (int m = 0; m < 4; ++m)
; #pragma unroll
;                 for (int n = 0; n < 2; ++n) acc[a][b][m][n] = (f32x4){0.f, 0.f, 0.f, 0.f};
;     bf16x8 At[4][2], B0[2][2], B1[2][2];
;     const char* cA = (const char*)g.A + (size_t)cur.pm * tstepA + (size_t)cur.pn * g.a_pn_off * 2; const char* cB = (const char*)g.Bt + (size_t)cur.pn * tstepB;
;     PG8_STAGE(PG8_SB(0, 0), cB, voffB); PG8_STAGE(PG8_SA(0, 0), cA, voffA); PG8_STAGE(PG8_SB(0, 1), cB + hstepB, voffB); PG8_STAGE(PG8_SA(0, 1), cA + hstepA, voffA);
;     if (wr == 1) PG8_BAR;
;     PG8_WAIT_V(4); PG8_BAR;
;     PG8_STAGE(PG8_SB(1, 0), cB + kstep, voffB); PG8_STAGE(PG8_SA(1, 0), cA + kstep, voffA); PG8_STAGE(PG8_SB(1, 1), cB + hstepB + kstep, voffB);
;     PG8_WAIT_V(6); PG8_BAR;
;     for (;;) {
;         const bool has_next = S.next(ui + 1, nxt);
;         const char* nA = has_next ? (const char*)g.A + (size_t)nxt.pm * tstepA + (size_t)nxt.pn * g.a_pn_off * 2 : cA; const char* nB = has_next ? (const char*)g.Bt + (size_t)nxt.pn * tstepB : cB;
;         for (int t = 0; t < nt; t += 2) {
;             const bool last = (t == nt - 2);
;             const char* a1 = cA + (size_t)(t + 1) * kstep;
;             const char* a2 = last ? nA : cA + (size_t)(t + 2) * kstep; const char* b2 = last ? nB : cB + (size_t)(t + 2) * kstep;
.LBB0_2618:
	s_ashr_i32 s27, s26, 31
	s_lshl_b64 s[28:29], s[26:27], 19
	s_add_u32 s28, s70, s28
	s_addc_u32 s29, s71, s29
	s_ashr_i32 s25, s24, 31
	s_lshl_b64 s[30:31], s[24:25], 19
	s_add_u32 s30, s18, s30
	v_pk_mov_b32 v[0:1], 0, 0
	v_cmp_lt_i64_e64 s[12:13], s[12:13], v[164:165]
	s_addc_u32 s31, s19, s31
	s_and_b64 vcc, exec, s[8:9]
	v_pk_mov_b32 v[2:3], 0, 0
	v_pk_mov_b32 v[4:5], 0, 0
	v_pk_mov_b32 v[6:7], 0, 0
	v_pk_mov_b32 v[8:9], 0, 0
	v_pk_mov_b32 v[10:11], 0, 0
	v_pk_mov_b32 v[12:13], 0, 0
	v_pk_mov_b32 v[14:15], 0, 0
	v_pk_mov_b32 v[16:17], 0, 0
	v_pk_mov_b32 v[18:19], 0, 0
	v_pk_mov_b32 v[20:21], 0, 0
	v_pk_mov_b32 v[22:23], 0, 0
	v_pk_mov_b32 v[24:25], 0, 0
	v_pk_mov_b32 v[26:27], 0, 0
	v_pk_mov_b32 v[28:29], 0, 0
	v_pk_mov_b32 v[30:31], 0, 0
	v_pk_mov_b32 v[32:33], 0, 0
	v_pk_mov_b32 v[34:35], 0, 0
	v_pk_mov_b32 v[36:37], 0, 0
	v_pk_mov_b32 v[38:39], 0, 0
	v_pk_mov_b32 v[40:41], 0, 0
	v_pk_mov_b32 v[42:43], 0, 0
	v_pk_mov_b32 v[44:45], 0, 0
	v_pk_mov_b32 v[46:47], 0, 0
	v_pk_mov_b32 v[48:49], 0, 0
	v_pk_mov_b32 v[50:51], 0, 0
	v_pk_mov_b32 v[52:53], 0, 0
	v_pk_mov_b32 v[54:55], 0, 0
	v_pk_mov_b32 v[56:57], 0, 0
	v_pk_mov_b32 v[58:59], 0, 0
	v_pk_mov_b32 v[60:61], 0, 0
	v_pk_mov_b32 v[62:63], 0, 0
	v_pk_mov_b32 v[64:65], 0, 0
	v_pk_mov_b32 v[66:67], 0, 0
	v_pk_mov_b32 v[68:69], 0, 0
	v_pk_mov_b32 v[70:71], 0, 0
	v_pk_mov_b32 v[72:73], 0, 0
	v_pk_mov_b32 v[74:75], 0, 0
	v_pk_mov_b32 v[76:77], 0, 0
	v_pk_mov_b32 v[78:79], 0, 0
	v_pk_mov_b32 v[80:81], 0, 0
	v_pk_mov_b32 v[82:83], 0, 0
	v_pk_mov_b32 v[84:85], 0, 0
	v_pk_mov_b32 v[86:87], 0, 0
	v_pk_mov_b32 v[88:89], 0, 0
	v_pk_mov_b32 v[90:91], 0, 0
	v_pk_mov_b32 v[92:93], 0, 0
	v_pk_mov_b32 v[94:95], 0, 0
	v_pk_mov_b32 v[96:97], 0, 0
	v_pk_mov_b32 v[98:99], 0, 0
	v_pk_mov_b32 v[100:101], 0, 0
	v_pk_mov_b32 v[102:103], 0, 0
	v_pk_mov_b32 v[104:105], 0, 0
	v_pk_mov_b32 v[106:107], 0, 0
	v_pk_mov_b32 v[108:109], 0, 0
	v_pk_mov_b32 v[110:111], 0, 0
	v_pk_mov_b32 v[112:113], 0, 0
	v_pk_mov_b32 v[114:115], 0, 0
	v_pk_mov_b32 v[116:117], 0, 0
	v_pk_mov_b32 v[118:119], 0, 0
	v_pk_mov_b32 v[120:121], 0, 0
	v_pk_mov_b32 v[122:123], 0, 0
	v_pk_mov_b32 v[124:125], 0, 0
	v_pk_mov_b32 v[126:127], 0, 0
	s_waitcnt lgkmcnt(0)
	s_cbranch_vccnz .LBB0_2621
	s_and_b64 s[12:13], s[12:13], exec
	s_cselect_b32 s25, s29, s41
	s_cselect_b32 s27, s28, s40
	s_cselect_b32 s64, s31, s39
	s_cselect_b32 s65, s30, s38
	s_add_u32 s12, s40, 0x40080
	s_addc_u32 s13, s41, 0
	s_add_u32 s76, s38, 0x100
	s_addc_u32 s77, s39, 0
	s_mov_b32 s38, 0
